# mLSTM pre-pass (ploc): k fragments hoisted out of the lt loop, q loads of an lt step issued together (was ~14 dependent memory round trips per step)
# baseline (speedup 1.0000x reference)
.LBB0_298:
	s_or_b32 s1, s0, s93
	s_cmp_lg_u32 s1, s76
	s_cbranch_scc1 .LBB0_297
	s_and_b32 s1, s27, 63
	s_lshl_b32 s1, s1, 6
	s_add_i32 s70, s0, s94
	s_add_i32 s4, s26, s1
	s_lshl_b32 s1, s70, 6
	s_and_b32 s1, s1, 0xfc0
	v_mov_b32_e32 v44, v137
	s_or_b32 s72, s1, s95
	s_ashr_i32 s5, s4, 31
	v_mov_b64_e32 v[2:3], s[34:35]
	v_add_u32_e32 v1, s72, v44
	s_movk_i32 s1, 0x1800
	s_lshl_b64 s[48:49], s[4:5], 11
	v_mad_i64_i32 v[2:3], s[4:5], v1, s1, v[2:3]
	v_lshl_add_u64 v[2:3], v[2:3], 0, s[16:17]
	s_movk_i32 s1, 0x1000
	v_add_co_u32_e32 v2, vcc, s1, v2
	global_load_dword v4, v25, s[24:25]
	s_nop 0
	v_addc_co_u32_e32 v3, vcc, 0, v3, vcc
	global_load_ushort v1, v[2:3], off offset:1584
	s_mov_b32 s4, 0xbfb8aa3b
	global_load_ushort v2, v[2:3], off offset:1592
	v_ashrrev_i32_e32 v0, 4, v44
	global_load_dword v3, v25, s[44:45]
	s_ashr_i32 s71, s70, 31
	v_lshlrev_b32_e32 v46, 3, v0
	v_ashrrev_i32_e32 v45, 31, v44
	v_add_u32_e32 v90, 32, v46
	v_and_b32_e32 v99, 15, v44
	v_ashrrev_i32_e32 v47, 31, v46
	s_mov_b32 s1, 0
	v_or_b32_e32 v100, 3, v46
	v_or_b32_e32 v101, 4, v46
	v_or_b32_e32 v102, 5, v46
	v_or_b32_e32 v103, 6, v46
	v_or_b32_e32 v104, 7, v46
	v_add_u32_e32 v105, 33, v46
	v_add_u32_e32 v106, 34, v46
	v_add_u32_e32 v107, 35, v46
	v_add_u32_e32 v108, 36, v46
	v_add_u32_e32 v109, 37, v46
	v_add_u32_e32 v110, 38, v46
	v_add_u32_e32 v111, 39, v46
	v_mov_b32_e32 v60, v44
	s_waitcnt vmcnt(2)
	v_lshlrev_b32_e32 v1, 16, v1
	v_add_f32_e32 v1, v4, v1
	s_waitcnt vmcnt(1)
	v_lshlrev_b32_e32 v2, 16, v2
	s_waitcnt vmcnt(0)
	v_add_f32_e32 v2, v3, v2
	v_min_f32_e32 v4, 0, v2
	v_mul_f32_e64 v2, |v2|, s4
	v_exp_f32_e32 v5, v2
	s_nop 0
	v_add_f32_e32 v6, 1.0, v5
	v_add_f32_e32 v2, -1.0, v6
	v_sub_f32_e32 v3, v2, v6
	v_add_f32_e32 v3, 1.0, v3
	v_sub_f32_e32 v2, v5, v2
	v_add_f32_e32 v7, v2, v3
	v_frexp_mant_f32_e32 v2, v6
	v_cmp_gt_f32_e32 vcc, s87, v2
	v_cvt_f64_f32_e32 v[2:3], v6
	v_frexp_exp_i32_f64_e32 v2, v[2:3]
	v_subbrev_co_u32_e32 v2, vcc, 0, v2, vcc
	v_sub_u32_e32 v3, 0, v2
	v_ldexp_f32 v6, v6, v3
	v_ldexp_f32 v3, v7, v3
	v_add_f32_e32 v7, -1.0, v6
	v_add_f32_e32 v8, 1.0, v7
	v_sub_f32_e32 v8, v6, v8
	v_add_f32_e32 v8, v3, v8
	v_add_f32_e32 v9, v7, v8
	v_sub_f32_e32 v7, v9, v7
	v_sub_f32_e32 v7, v8, v7
	v_add_f32_e32 v8, 1.0, v6
	v_add_f32_e32 v10, -1.0, v8
	v_sub_f32_e32 v6, v6, v10
	v_add_f32_e32 v3, v3, v6
	v_add_f32_e32 v6, v8, v3
	v_sub_f32_e32 v8, v6, v8
	v_sub_f32_e32 v3, v3, v8
	v_rcp_f32_e32 v8, v6
	v_cvt_f32_i32_e32 v2, v2
	v_cmp_neq_f32_e32 vcc, s89, v5
	v_mul_f32_e32 v10, v9, v8
	v_mul_f32_e32 v11, v6, v10
	v_fma_f32 v12, v10, v6, -v11
	v_fmac_f32_e32 v12, v10, v3
	v_add_f32_e32 v13, v11, v12
	v_sub_f32_e32 v14, v9, v13
	v_sub_f32_e32 v9, v9, v14
	v_sub_f32_e32 v11, v13, v11
	v_sub_f32_e32 v9, v9, v13
	v_add_f32_e32 v7, v7, v9
	v_sub_f32_e32 v9, v11, v12
	v_add_f32_e32 v7, v9, v7
	v_add_f32_e32 v9, v14, v7
	v_mul_f32_e32 v11, v8, v9
	v_mul_f32_e32 v12, v6, v11
	v_fma_f32 v6, v11, v6, -v12
	v_fmac_f32_e32 v6, v11, v3
	v_sub_f32_e32 v3, v14, v9
	v_add_f32_e32 v3, v7, v3
	v_add_f32_e32 v7, v12, v6
	v_sub_f32_e32 v13, v9, v7
	v_sub_f32_e32 v9, v9, v13
	v_sub_f32_e32 v12, v7, v12
	v_sub_f32_e32 v7, v9, v7
	v_add_f32_e32 v3, v3, v7
	v_sub_f32_e32 v6, v12, v6
	v_add_f32_e32 v3, v6, v3
	v_add_f32_e32 v6, v10, v11
	v_add_f32_e32 v3, v13, v3
	v_sub_f32_e32 v7, v6, v10
	v_mul_f32_e32 v3, v8, v3
	v_sub_f32_e32 v7, v11, v7
	v_add_f32_e32 v3, v7, v3
	v_mul_f32_e32 v10, 0x3f317218, v2
	v_add_f32_e32 v7, v6, v3
	v_fma_f32 v11, v2, s88, -v10
	v_mul_f32_e32 v8, v7, v7
	v_fmac_f32_e32 v11, 0xb102e308, v2
	v_sub_f32_e32 v2, v7, v6
	v_fmamk_f32 v9, v8, 0x3e9b6dac, v76
	v_sub_f32_e32 v2, v3, v2
	v_add_f32_e32 v3, v10, v11
	v_fmaak_f32 v9, v8, v9, 0x3f2aaada
	v_sub_f32_e32 v6, v3, v10
	v_ldexp_f32 v10, v7, 1
	v_mul_f32_e32 v7, v7, v8
	v_mul_f32_e32 v7, v7, v9
	v_add_f32_e32 v8, v10, v7
	v_sub_f32_e32 v9, v8, v10
	v_ldexp_f32 v2, v2, 1
	v_sub_f32_e32 v7, v7, v9
	v_add_f32_e32 v2, v2, v7
	v_add_f32_e32 v7, v8, v2
	v_sub_f32_e32 v8, v7, v8
	v_sub_f32_e32 v2, v2, v8
	v_add_f32_e32 v8, v3, v7
	v_sub_f32_e32 v9, v8, v3
	v_sub_f32_e32 v10, v8, v9
	v_sub_f32_e32 v6, v11, v6
	v_sub_f32_e32 v3, v3, v10
	v_sub_f32_e32 v7, v7, v9
	v_add_f32_e32 v3, v7, v3
	v_add_f32_e32 v7, v6, v2
	v_sub_f32_e32 v9, v7, v6
	v_sub_f32_e32 v10, v7, v9
	v_sub_f32_e32 v6, v6, v10
	v_sub_f32_e32 v2, v2, v9
	v_add_f32_e32 v3, v7, v3
	v_add_f32_e32 v2, v2, v6
	v_add_f32_e32 v6, v8, v3
	v_sub_f32_e32 v7, v6, v8
	v_sub_f32_e32 v3, v3, v7
	v_add_f32_e32 v2, v2, v3
	v_add_f32_e32 v2, v6, v2
	v_cndmask_b32_e32 v2, v77, v2, vcc
	v_cmp_ngt_f32_e32 vcc, -1.0, v5
	v_add_u32_e32 v3, -1, v80
	s_nop 0
	v_cndmask_b32_e32 v2, v78, v2, vcc
	v_cmp_neq_f32_e32 vcc, -1.0, v5
	s_nop 1
	v_cndmask_b32_e32 v2, v79, v2, vcc
	v_cmp_lt_f32_e64 vcc, |v5|, s90
	s_nop 1
	v_cndmask_b32_e32 v2, v2, v5, vcc
	v_sub_f32_e32 v4, v4, v2
	v_and_b32_e32 v2, 64, v80
	v_cmp_lt_i32_e32 vcc, v3, v2
	s_nop 1
	v_cndmask_b32_e32 v3, v3, v80, vcc
	v_lshlrev_b32_e32 v3, 2, v3
	ds_bpermute_b32 v5, v3, v4
	v_cmp_gt_i32_e32 vcc, 1, v44
	s_waitcnt lgkmcnt(0)
	v_add_f32_e32 v5, v4, v5
	v_cndmask_b32_e32 v5, v5, v4, vcc
	v_add_u32_e32 v4, -2, v80
	v_cmp_lt_i32_e64 s[4:5], v4, v2
	s_nop 1
	v_cndmask_b32_e64 v4, v4, v80, s[4:5]
	v_lshlrev_b32_e32 v4, 2, v4
	ds_bpermute_b32 v6, v4, v5
	v_cmp_gt_i32_e64 s[4:5], 2, v44
	s_waitcnt lgkmcnt(0)
	v_add_f32_e32 v6, v5, v6
	v_cndmask_b32_e64 v6, v6, v5, s[4:5]
	v_add_u32_e32 v5, -4, v80
	v_cmp_lt_i32_e64 s[6:7], v5, v2
	s_nop 1
	v_cndmask_b32_e64 v5, v5, v80, s[6:7]
	v_lshlrev_b32_e32 v5, 2, v5
	ds_bpermute_b32 v7, v5, v6
	v_cmp_gt_i32_e64 s[6:7], 4, v44
	s_waitcnt lgkmcnt(0)
	v_add_f32_e32 v7, v6, v7
	v_cndmask_b32_e64 v7, v7, v6, s[6:7]
	v_add_u32_e32 v6, -8, v80
	v_cmp_lt_i32_e64 s[8:9], v6, v2
	s_nop 1
	v_cndmask_b32_e64 v6, v6, v80, s[8:9]
	v_lshlrev_b32_e32 v6, 2, v6
	ds_bpermute_b32 v8, v6, v7
	v_cmp_gt_i32_e64 s[8:9], 8, v44
	s_waitcnt lgkmcnt(0)
	v_add_f32_e32 v8, v7, v8
	v_cndmask_b32_e64 v7, v8, v7, s[8:9]
	v_add_u32_e32 v8, -16, v80
	v_cmp_lt_i32_e64 s[10:11], v8, v2
	s_nop 1
	v_cndmask_b32_e64 v8, v8, v80, s[10:11]
	v_lshlrev_b32_e32 v8, 2, v8
	ds_bpermute_b32 v9, v8, v7
	v_cmp_gt_i32_e64 s[10:11], 16, v44
	s_waitcnt lgkmcnt(0)
	v_add_f32_e32 v9, v7, v9
	v_cndmask_b32_e64 v7, v9, v7, s[10:11]
	v_subrev_u32_e32 v9, 32, v80
	v_cmp_lt_i32_e64 s[12:13], v9, v2
	s_nop 1
	v_cndmask_b32_e64 v9, v9, v80, s[12:13]
	v_lshlrev_b32_e32 v9, 2, v9
	ds_bpermute_b32 v10, v9, v7
	v_cmp_gt_i32_e64 s[12:13], 32, v44
	s_waitcnt lgkmcnt(0)
	v_add_f32_e32 v10, v7, v10
	v_cndmask_b32_e64 v7, v10, v7, s[12:13]
	v_sub_f32_e32 v1, v1, v7
	ds_bpermute_b32 v3, v3, v1
	s_waitcnt lgkmcnt(0)
	v_max_f32_e32 v3, v3, v3
	v_max_f32_e32 v3, v1, v3
	v_cndmask_b32_e32 v3, v3, v1, vcc
	ds_bpermute_b32 v4, v4, v3
	s_waitcnt lgkmcnt(0)
	v_max_f32_e32 v4, v4, v4
	v_max_f32_e32 v4, v3, v4
	v_cndmask_b32_e64 v3, v4, v3, s[4:5]
	ds_bpermute_b32 v4, v5, v3
	s_mul_i32 s4, s70, 0x300
	s_mul_hi_i32 s5, s70, 0x300
	s_add_u32 s4, s81, s4
	s_addc_u32 s5, s82, s5
	s_waitcnt lgkmcnt(0)
	v_max_f32_e32 v4, v4, v4
	v_max_f32_e32 v4, v3, v4
	v_cndmask_b32_e64 v3, v4, v3, s[6:7]
	ds_bpermute_b32 v4, v6, v3
	s_ashr_i32 s73, s72, 31
	s_lshl_b64 s[6:7], s[72:73], 11
	s_waitcnt lgkmcnt(0)
	v_max_f32_e32 v4, v4, v4
	v_max_f32_e32 v4, v3, v4
	v_cndmask_b32_e64 v3, v4, v3, s[8:9]
	ds_bpermute_b32 v4, v8, v3
	s_waitcnt lgkmcnt(0)
	v_max_f32_e32 v4, v4, v4
	v_max_f32_e32 v4, v3, v4
	v_cndmask_b32_e64 v3, v4, v3, s[10:11]
	ds_bpermute_b32 v4, v9, v3
	v_max_f32_e32 v5, v3, v3
	s_waitcnt lgkmcnt(0)
	v_max_f32_e32 v4, v4, v4
	v_max_f32_e32 v4, v5, v4
	v_cndmask_b32_e64 v81, v4, v3, s[12:13]
	v_lshl_add_u64 v[4:5], v[44:45], 2, s[4:5]
	s_lshl_b64 s[4:5], s[70:71], 13
	v_and_or_b32 v3, v46, 56, v2
	v_and_or_b32 v2, v90, 56, v2
	s_add_u32 s4, s84, s4
	v_lshlrev_b32_e32 v3, 2, v3
	v_lshlrev_b32_e32 v2, 2, v2
	global_store_dword v[4:5], v1, off
	global_store_dword v[4:5], v7, off offset:256
	global_store_dword v[4:5], v81, off offset:512
	s_addc_u32 s5, s85, s5
	s_lshl_b64 s[8:9], s[70:71], 14
	ds_bpermute_b32 v82, v3, v1
	ds_bpermute_b32 v83, v3, v1 offset:4
	ds_bpermute_b32 v84, v3, v1 offset:8
	ds_bpermute_b32 v85, v3, v1 offset:12
	ds_bpermute_b32 v86, v3, v1 offset:16
	ds_bpermute_b32 v87, v3, v1 offset:20
	ds_bpermute_b32 v88, v3, v1 offset:24
	ds_bpermute_b32 v89, v3, v1 offset:28
	ds_bpermute_b32 v91, v2, v1
	ds_bpermute_b32 v92, v2, v1 offset:4
	ds_bpermute_b32 v93, v2, v1 offset:8
	ds_bpermute_b32 v94, v2, v1 offset:12
	ds_bpermute_b32 v95, v2, v1 offset:16
	ds_bpermute_b32 v96, v2, v1 offset:20
	ds_bpermute_b32 v97, v2, v1 offset:24
	ds_bpermute_b32 v98, v2, v1 offset:28
	v_lshlrev_b32_e32 v1, 1, v44
	v_and_b32_e32 v2, 3, v44
	s_add_u32 s10, s96, s6
	v_and_or_b32 v1, v1, 24, v2
	s_addc_u32 s11, s97, s7
	v_lshlrev_b32_e32 v24, 11, v1
	v_lshl_add_u64 v[2:3], s[10:11], 0, v[24:25]
	v_lshlrev_b64 v[4:5], 1, v[46:47]
	v_lshlrev_b32_e32 v24, 11, v99
	v_lshl_add_u64 v[48:49], v[2:3], 0, v[4:5]
	v_ashrrev_i32_e32 v1, 31, v0
	v_lshl_add_u64 v[2:3], s[48:49], 0, v[24:25]
	v_lshlrev_b64 v[0:1], 3, v[0:1]
	v_lshl_add_u64 v[2:3], v[2:3], 0, v[4:5]
	v_sub_co_u32_e32 v0, vcc, v2, v0
	s_add_u32 s6, s38, s8
	s_nop 0
	v_subb_co_u32_e32 v1, vcc, v3, v1, vcc
	v_lshl_add_u64 v[58:59], s[46:47], 0, v[0:1]
	v_lshlrev_b32_e32 v0, 2, v80
	v_lshlrev_b32_e32 v1, 2, v99
	s_addc_u32 s7, s39, s9
	v_or_b32_e32 v47, 2, v46
	v_lshl_add_u64 v[50:51], v[48:49], 0, s[18:19]
	v_lshl_add_u64 v[52:53], v[48:49], 0, s[20:21]
	v_lshl_add_u64 v[54:55], v[48:49], 0, s[22:23]
	v_lshl_add_u64 v[56:57], s[46:47], 0, v[2:3]
	v_and_or_b32 v24, v0, s77, v1
	global_load_dwordx4 v[186:189], v[48:49], off offset:256
	global_load_dwordx4 v[190:193], v[48:49], off offset:320
	global_load_dwordx4 v[194:197], v[48:49], off offset:384
	global_load_dwordx4 v[198:201], v[48:49], off offset:448
	global_load_dwordx4 v[202:205], v[50:51], off
	global_load_dwordx4 v[206:209], v[50:51], off offset:64
	global_load_dwordx4 v[210:213], v[50:51], off offset:128
	global_load_dwordx4 v[214:217], v[50:51], off offset:192
	global_load_dwordx4 v[218:221], v[52:53], off
	global_load_dwordx4 v[222:225], v[52:53], off offset:64
	global_load_dwordx4 v[226:229], v[52:53], off offset:128
	global_load_dwordx4 v[230:233], v[52:53], off offset:192
	global_load_dwordx4 v[234:237], v[54:55], off
	global_load_dwordx4 v[238:241], v[54:55], off offset:64
	global_load_dwordx4 v[242:245], v[54:55], off offset:128
	global_load_dwordx4 v[246:249], v[54:55], off offset:192
	s_mov_b64 s[8:9], 0
	s_branch .LBB0_301

.LBB0_301:
	s_nop 0
	v_lshl_add_u64 v[0:1], v[56:57], 0, s[8:9]
	v_add_co_u32_e32 v16, vcc, 0x4000000, v0
	v_lshl_add_u64 v[4:5], v[58:59], 0, s[8:9]
	s_nop 0
	v_addc_co_u32_e32 v17, vcc, 0, v1, vcc
	v_add_co_u32_e32 v20, vcc, 0x4000000, v4
	global_load_dwordx4 v[0:3], v[16:17], off
	s_nop 0
	v_addc_co_u32_e32 v21, vcc, 0, v5, vcc
	global_load_dwordx4 v[4:7], v[16:17], off offset:64
	global_load_dwordx4 v[12:15], v[16:17], off offset:128
	global_load_dwordx4 v[166:169], v[16:17], off offset:192
	global_load_dwordx2 v[170:171], v[20:21], off
	global_load_dwordx2 v[172:173], v[20:21], off offset:32
	global_load_dwordx2 v[174:175], v[20:21], off offset:64
	global_load_dwordx2 v[176:177], v[20:21], off offset:96
	global_load_dwordx2 v[178:179], v[20:21], off offset:128
	global_load_dwordx2 v[180:181], v[20:21], off offset:160
	global_load_dwordx2 v[182:183], v[20:21], off offset:192
	global_load_dwordx2 v[184:185], v[20:21], off offset:224
	v_ashrrev_i32_e32 v45, 31, v44
	v_lshl_add_u64 v[22:23], v[44:45], 4, s[6:7]
	ds_bpermute_b32 v112, v24, v81
	v_cmp_le_i32_e32 vcc, v46, v99
	s_cmp_gt_u32 s1, 1
	s_cselect_b64 s[10:11], -1, 0
	s_cmp_lt_u32 s1, 2
	s_waitcnt lgkmcnt(0)
	v_sub_f32_e32 v61, v86, v112
	v_mul_f32_e32 v61, 0x3fb8aa3b, v61
	v_exp_f32_e32 v61, v61
	s_waitcnt vmcnt(0)
	global_store_dwordx4 v[22:23], v[170:173], off
	global_store_dwordx4 v[22:23], v[174:177], off offset:1024
	global_store_dwordx4 v[22:23], v[178:181], off offset:2048
	global_store_dwordx4 v[22:23], v[182:185], off offset:3072
	v_mov_b32_e32 v16, v166
	v_mov_b32_e32 v17, v167
	v_mov_b32_e32 v18, v168
	v_mov_b32_e32 v19, v169
	v_mfma_f32_16x16x32_bf16 v[8:11], v[186:189], v[0:3], 0
	v_mfma_f32_16x16x32_bf16 v[8:11], v[190:193], v[4:7], v[8:11]
	v_mfma_f32_16x16x32_bf16 v[8:11], v[194:197], v[12:15], v[8:11]
	v_mfma_f32_16x16x32_bf16 v[8:11], v[198:201], v[16:19], v[8:11]
	v_sub_f32_e32 v20, v82, v112
	v_mul_f32_e32 v20, 0x3fb8aa3b, v20
	v_exp_f32_e32 v20, v20
	s_nop 4
	v_mul_f32_e32 v20, v20, v8
	v_cndmask_b32_e32 v45, 0, v20, vcc
	v_sub_f32_e32 v20, v83, v112
	v_mul_f32_e32 v20, 0x3fb8aa3b, v20
	v_exp_f32_e32 v20, v20
	v_cmp_lt_i32_e32 vcc, v46, v99
	v_mov_b32_e32 v8, 0
	v_mul_f32_e32 v9, v20, v9
	v_sub_f32_e32 v20, v84, v112
	v_mul_f32_e32 v20, 0x3fb8aa3b, v20
	v_exp_f32_e32 v20, v20
	v_cndmask_b32_e32 v9, 0, v9, vcc
	v_cmp_le_i32_e32 vcc, v47, v99
	v_mul_f32_e32 v10, v20, v10
	v_sub_f32_e32 v20, v85, v112
	v_mul_f32_e32 v20, 0x3fb8aa3b, v20
	v_exp_f32_e32 v20, v20
	v_cndmask_b32_e32 v10, 0, v10, vcc
	v_cmp_le_i32_e32 vcc, v100, v99
	v_mul_f32_e32 v11, v20, v11
	v_cndmask_b32_e32 v11, 0, v11, vcc
	v_cmp_le_i32_e32 vcc, v101, v99
	v_mfma_f32_16x16x32_bf16 v[20:23], v[202:205], v[0:3], 0
	v_mfma_f32_16x16x32_bf16 v[20:23], v[206:209], v[4:7], v[20:23]
	v_mfma_f32_16x16x32_bf16 v[20:23], v[210:213], v[12:15], v[20:23]
	v_mfma_f32_16x16x32_bf16 v[20:23], v[214:217], v[16:19], v[20:23]
	s_nop 7
	v_mul_f32_e32 v20, v61, v20
	v_cndmask_b32_e32 v61, 0, v20, vcc
	v_sub_f32_e32 v20, v87, v112
	v_mul_f32_e32 v20, 0x3fb8aa3b, v20
	v_exp_f32_e32 v20, v20
	v_cmp_le_i32_e32 vcc, v102, v99
	v_mul_f32_e32 v20, v20, v21
	s_nop 0
	v_cndmask_b32_e32 v62, 0, v20, vcc
	v_sub_f32_e32 v20, v88, v112
	v_mul_f32_e32 v20, 0x3fb8aa3b, v20
	v_exp_f32_e32 v20, v20
	v_cmp_le_i32_e32 vcc, v103, v99
	v_cvt_pk_bf16_f32 v21, v10, v11
	v_mul_f32_e32 v20, v20, v22
	s_nop 0
	v_cndmask_b32_e32 v63, 0, v20, vcc
	v_sub_f32_e32 v20, v89, v112
	v_mul_f32_e32 v20, 0x3fb8aa3b, v20
	v_exp_f32_e32 v20, v20
	v_cmp_le_i32_e32 vcc, v104, v99
	v_cvt_pk_bf16_f32 v22, v61, v62
	v_ashrrev_i32_e32 v61, 31, v60
	v_mul_f32_e32 v20, v20, v23
	v_cndmask_b32_e32 v23, 0, v20, vcc
	v_cvt_pk_bf16_f32 v20, v45, v9
	v_cvt_pk_bf16_f32 v23, v63, v23
	v_lshl_add_u64 v[62:63], v[60:61], 4, s[4:5]
	global_store_dwordx4 v[62:63], v[20:23], off
	s_nop 1
	v_mov_b32_e32 v20, 0
	v_mov_b32_e32 v21, 0
	v_mov_b32_e32 v22, 0
	v_mov_b32_e32 v23, 0
	s_cbranch_scc1 .LBB0_303
	v_mfma_f32_16x16x32_bf16 v[20:23], v[218:221], v[0:3], 0
	v_mfma_f32_16x16x32_bf16 v[20:23], v[222:225], v[4:7], v[20:23]
	v_mfma_f32_16x16x32_bf16 v[20:23], v[226:229], v[12:15], v[20:23]
	v_mfma_f32_16x16x32_bf16 v[20:23], v[230:233], v[16:19], v[20:23]
.LBB0_303:
	s_andn2_b64 vcc, exec, s[10:11]
	v_mov_b32_e32 v9, 0
	v_mov_b32_e32 v10, 0
	v_mov_b32_e32 v11, 0
	s_cbranch_vccnz .LBB0_300
	v_mfma_f32_16x16x32_bf16 v[0:3], v[234:237], v[0:3], 0
	v_mfma_f32_16x16x32_bf16 v[0:3], v[238:241], v[4:7], v[0:3]
	v_mfma_f32_16x16x32_bf16 v[0:3], v[242:245], v[12:15], v[0:3]
	v_mfma_f32_16x16x32_bf16 v[8:11], v[246:249], v[16:19], v[0:3]
	s_branch .LBB0_300
